# grid barrier: wave 1 of each workgroup issues an early L2 write-back behind the arrival barrier so the XCD leader's write-back finds less dirty data
# baseline (speedup 1.0000x reference)
.Lwarm_skip_1:
	s_cmp_eq_u32 s33, 64
	s_cbranch_scc0 .Lwb_skip
	buffer_wbl2 sc1
